# prologue: transposes on the idle WGs 224-255; fold item issues its first w_in chunk loads before the G MFMA loop and the peeled 8th staging loads with the other seven
# baseline (speedup 1.0000x reference)
; #define LAS __attribute__((address_space(3)))
; __device__ __forceinline__ void p0_fold_item(const Params& p, LAS unsigned char* lds, int item) {
;     ...
;     for (int u = tid; u < 4096; u += NTHREADS) *(LAS f32x4*)(Wf + 4 * u) = *(const f32x4*)(p.w_four + (size_t)g * 16384 + 4 * u);
;     __syncthreads();
;     {
;         const int mt = w >> 1, nt0 = (w & 1) * 2, li = lane & 31, lk = lane >> 5, c = mt * 32 + li;
;         f32x16 acc0, acc1;
; #pragma unroll
;         for (int r = 0; r < 16; ++r) { acc0[r] = 0.f; acc1[r] = 0.f; }
; #pragma unroll 4
;         for (int ks = 0; ks < 64; ++ks) { const int e = 2 * ks + lk; const float ang = (float)((c * e) & 127) * (1.0f / 128.0f);
;             const float a = (which ? __builtin_amdgcn_sinf(ang) : __builtin_amdgcn_cosf(ang)) * 0.08838834764831845f;
;             const float b0 = Wf[e * 128 + nt0 * 32 + li], b1 = Wf[e * 128 + nt0 * 32 + 32 + li];
;             acc0 = __builtin_amdgcn_mfma_f32_32x32x2f32(a, b0, acc0, 0, 0, 0); acc1 = __builtin_amdgcn_mfma_f32_32x32x2f32(a, b1, acc1, 0, 0, 0); }
; #pragma unroll
;         for (int r = 0; r < 16; ++r) { const int row = mt * 32 + (r & 3) + 8 * (r >> 2) + 4 * lk; Gm[row * 128 + nt0 * 32 + li] = acc0[r]; Gm[row * 128 + nt0 * 32 + 32 + li] = acc1[r]; }
;     }
;     for (int sub = 0; sub < 2; ++sub) { const int i0 = ib + sub * 32;
;     for (int u = tid; u < 4096; u += NTHREADS) { const int il = u >> 7, c = u & 127; wt[il * 129 + c] = p.w_in[(size_t)(i0 + il) * 2048 + g * 128 + c]; }
.LBB0_36:
	s_bfe_u32 s11, s10, 0x20004
	s_lshl_b32 s14, s11, 16
	s_waitcnt lgkmcnt(0)
	s_add_u32 s16, s48, s14
	s_addc_u32 s17, s49, 0
	v_lshl_add_u64 v[0:1], s[16:17], 0, v[34:35]
	v_add_co_u32_e32 v6, vcc, 0x2000, v0
	global_load_dwordx4 v[2:5], v34, s[16:17]
	s_nop 0
	v_addc_co_u32_e32 v7, vcc, 0, v1, vcc
	v_add_co_u32_e32 v14, vcc, 0x6000, v0
	global_load_dwordx4 v[6:9], v[6:7], off
	s_nop 0
	global_load_dwordx4 v[10:13], v60, s[16:17]
	v_addc_co_u32_e32 v15, vcc, 0, v1, vcc
	v_add_co_u32_e32 v22, vcc, 0xa000, v0
	global_load_dwordx4 v[14:17], v[14:15], off
	s_nop 0
	global_load_dwordx4 v[18:21], v61, s[16:17]
	v_addc_co_u32_e32 v23, vcc, 0, v1, vcc
	global_load_dwordx4 v[22:25], v[22:23], off
	s_nop 0
	global_load_dwordx4 v[26:29], v62, s[16:17]
	v_add_co_u32_e32 v208, vcc, 0xe000, v0
	s_nop 1
	v_addc_co_u32_e32 v209, vcc, 0, v1, vcc
	s_and_saveexec_b64 s[98:99], s[4:5]
	global_load_dwordx4 v[204:207], v[208:209], off
	s_or_b64 exec, exec, s[98:99]
	s_waitcnt vmcnt(7)
	ds_write_b128 v41, v[2:5]
	s_waitcnt vmcnt(6)
	ds_write_b128 v41, v[6:9] offset:8192
	s_waitcnt vmcnt(5)
	ds_write_b128 v41, v[10:13] offset:16384
	s_waitcnt vmcnt(4)
	ds_write_b128 v41, v[14:17] offset:24576
	s_waitcnt vmcnt(3)
	ds_write_b128 v41, v[18:21] offset:32768
	s_waitcnt vmcnt(2)
	ds_write_b128 v41, v[22:25] offset:40960
	s_waitcnt vmcnt(1)
	ds_write_b128 v42, v[26:29]
	s_and_saveexec_b64 s[16:17], s[4:5]
	s_cbranch_execz .LBB0_38
	s_waitcnt vmcnt(0)
	ds_write_b128 v41, v[204:207] offset:57344
.LBB0_38:
	s_or_b64 exec, exec, s[16:17]
	s_lshl_b32 s98, s10, 6
	s_and_b32 s98, s98, 0x3c0
	s_lshl_b32 s11, s11, 7
	v_or_b32_e32 v212, s98, v44
	v_or_b32_e32 v213, s98, v45
	v_or_b32_e32 v214, s98, v46
	v_or_b32_e32 v215, s98, v47
	v_or_b32_e32 v216, s98, v48
	v_or_b32_e32 v217, s98, v49
	v_or_b32_e32 v218, s98, v50
	v_or_b32_e32 v219, s98, v51
	v_lshlrev_b32_e32 v212, 11, v212
	v_lshlrev_b32_e32 v213, 11, v213
	v_lshlrev_b32_e32 v214, 11, v214
	v_lshlrev_b32_e32 v215, 11, v215
	v_lshlrev_b32_e32 v216, 11, v216
	v_lshlrev_b32_e32 v217, 11, v217
	v_lshlrev_b32_e32 v218, 11, v218
	v_lshlrev_b32_e32 v219, 11, v219
	v_or3_b32 v212, v109, v212, s11
	v_or3_b32 v213, v109, v213, s11
	v_or3_b32 v214, v109, v214, s11
	v_or3_b32 v215, v109, v215, s11
	v_or3_b32 v216, v109, v216, s11
	v_or3_b32 v217, v109, v217, s11
	v_or3_b32 v218, v109, v218, s11
	v_or3_b32 v219, v109, v219, s11
	v_lshlrev_b32_e32 v212, 2, v212
	v_lshlrev_b32_e32 v213, 2, v213
	v_lshlrev_b32_e32 v214, 2, v214
	v_lshlrev_b32_e32 v215, 2, v215
	v_lshlrev_b32_e32 v216, 2, v216
	v_lshlrev_b32_e32 v217, 2, v217
	v_lshlrev_b32_e32 v218, 2, v218
	v_lshlrev_b32_e32 v219, 2, v219
	global_load_dword v212, v212, s[46:47]
	global_load_dword v213, v213, s[46:47]
	global_load_dword v214, v214, s[46:47]
	global_load_dword v215, v215, s[46:47]
	global_load_dword v216, v216, s[46:47]
	global_load_dword v217, v217, s[46:47]
	global_load_dword v218, v218, s[46:47]
	s_and_saveexec_b64 s[98:99], s[4:5]
	global_load_dword v219, v219, s[46:47]
	s_or_b64 exec, exec, s[98:99]
	v_mov_b32_e32 v0, 0
	s_cmp_lt_u32 s10, 64
	v_mov_b32_e32 v69, 0
	s_cselect_b64 vcc, -1, 0
	s_mov_b32 s14, 0
	v_mov_b32_e32 v1, v0
	v_mov_b32_e32 v2, v0
	v_mov_b32_e32 v3, v0
	v_mov_b32_e32 v4, v0
	v_mov_b32_e32 v5, v0
	v_mov_b32_e32 v6, v0
	v_mov_b32_e32 v7, v0
	v_mov_b32_e32 v8, v0
	v_mov_b32_e32 v9, v0
	v_mov_b32_e32 v10, v0
	v_mov_b32_e32 v11, v0
	v_mov_b32_e32 v12, v0
	v_mov_b32_e32 v13, v0
	v_mov_b32_e32 v14, v0
	v_mov_b32_e32 v15, v0
	v_mov_b32_e32 v16, v0
	v_mov_b32_e32 v17, v0
	v_mov_b32_e32 v18, v0
	v_mov_b32_e32 v19, v0
	v_mov_b32_e32 v20, v0
	v_mov_b32_e32 v21, v0
	v_mov_b32_e32 v22, v0
	v_mov_b32_e32 v23, v0
	v_mov_b32_e32 v24, v0
	v_mov_b32_e32 v25, v0
	v_mov_b32_e32 v26, v0
	v_mov_b32_e32 v27, v0
	v_mov_b32_e32 v28, v0
	v_mov_b32_e32 v29, v0
	v_mov_b32_e32 v30, v0
	v_mov_b32_e32 v31, v0
	s_waitcnt lgkmcnt(0)
	s_barrier
; __device__ __forceinline__ void p0_fold_item(const Params& p, LAS unsigned char* lds, int item) {
;     ...
; #pragma unroll 4
;         for (int ks = 0; ks < 64; ++ks) { const int e = 2 * ks + lk; const float ang = (float)((c * e) & 127) * (1.0f / 128.0f);
;             const float a = (which ? __builtin_amdgcn_sinf(ang) : __builtin_amdgcn_cosf(ang)) * 0.08838834764831845f;
;             const float b0 = Wf[e * 128 + nt0 * 32 + li], b1 = Wf[e * 128 + nt0 * 32 + 32 + li];
;             acc0 = __builtin_amdgcn_mfma_f32_32x32x2f32(a, b0, acc0, 0, 0, 0); acc1 = __builtin_amdgcn_mfma_f32_32x32x2f32(a, b1, acc1, 0, 0, 0); }
; #pragma unroll
;         for (int r = 0; r < 16; ++r) { const int row = mt * 32 + (r & 3) + 8 * (r >> 2) + 4 * lk; Gm[row * 128 + nt0 * 32 + li] = acc0[r]; Gm[row * 128 + nt0 * 32 + 32 + li] = acc1[r]; }
;     }
;     for (int sub = 0; sub < 2; ++sub) { const int i0 = ib + sub * 32;
;     for (int u = tid; u < 4096; u += NTHREADS) { const int il = u >> 7, c = u & 127; wt[il * 129 + c] = p.w_in[(size_t)(i0 + il) * 2048 + g * 128 + c]; }
.LBB0_39:
	v_add_u32_e32 v70, v57, v69
	v_and_b32_e32 v73, 0x7f, v70
	v_cvt_f32_ubyte0_e32 v73, v73
	v_mul_f32_e32 v73, 0x3c000000, v73
	v_sin_f32_e32 v74, v73
	v_cos_f32_e32 v73, v73
	v_add_u32_e32 v72, s14, v52
	ds_read2_b32 v[70:71], v72 offset1:32
	s_addk_i32 s14, 0x1000
	v_cndmask_b32_e32 v73, v74, v73, vcc
	v_mul_f32_e32 v73, 0x3db504f3, v73
	s_cmp_eq_u32 s14, 0x10000
	s_waitcnt lgkmcnt(0)
	v_mfma_f32_32x32x2_f32 v[0:15], v73, v70, v[0:15]
	v_add_u32_e32 v70, v56, v69
	v_and_b32_e32 v70, 0x7f, v70
	v_mfma_f32_32x32x2_f32 v[16:31], v73, v71, v[16:31]
	v_cvt_f32_ubyte0_e32 v73, v70
	v_mul_f32_e32 v73, 0x3c000000, v73
	v_sin_f32_e32 v74, v73
	v_cos_f32_e32 v73, v73
	v_add_u32_e32 v71, 0x400, v72
	ds_read2_b32 v[70:71], v71 offset1:32
	v_cndmask_b32_e32 v73, v74, v73, vcc
	v_mul_f32_e32 v73, 0x3db504f3, v73
	s_waitcnt lgkmcnt(0)
	s_nop 0
	v_mfma_f32_32x32x2_f32 v[0:15], v73, v70, v[0:15]
	v_add_u32_e32 v70, v55, v69
	v_and_b32_e32 v70, 0x7f, v70
	v_mfma_f32_32x32x2_f32 v[16:31], v73, v71, v[16:31]
	v_cvt_f32_ubyte0_e32 v73, v70
	v_mul_f32_e32 v73, 0x3c000000, v73
	v_sin_f32_e32 v74, v73
	v_cos_f32_e32 v73, v73
	v_add_u32_e32 v71, 0x800, v72
	ds_read2_b32 v[70:71], v71 offset1:32
	v_cndmask_b32_e32 v73, v74, v73, vcc
	v_mul_f32_e32 v73, 0x3db504f3, v73
	s_waitcnt lgkmcnt(0)
	s_nop 0
	v_mfma_f32_32x32x2_f32 v[0:15], v73, v70, v[0:15]
	v_add_u32_e32 v70, v53, v69
	v_and_b32_e32 v70, 0x7f, v70
	v_add_u32_e32 v69, v69, v54
	v_mfma_f32_32x32x2_f32 v[16:31], v73, v71, v[16:31]
	v_add_u32_e32 v71, 0xc00, v72
	v_cvt_f32_ubyte0_e32 v72, v70
	v_mul_f32_e32 v72, 0x3c000000, v72
	v_sin_f32_e32 v73, v72
	v_cos_f32_e32 v72, v72
	ds_read2_b32 v[70:71], v71 offset1:32
	v_cndmask_b32_e32 v72, v73, v72, vcc
	v_mul_f32_e32 v72, 0x3db504f3, v72
	s_waitcnt lgkmcnt(0)
	s_nop 0
	v_mfma_f32_32x32x2_f32 v[0:15], v72, v70, v[0:15]
	v_mfma_f32_32x32x2_f32 v[16:31], v72, v71, v[16:31]
	s_cbranch_scc0 .LBB0_39
	s_lshl_b32 s14, s10, 6
	s_and_b32 s19, s14, 0x3c0
	v_add_u32_e32 v76, v117, v116
	ds_write2_b32 v76, v0, v16 offset1:32
	ds_write2_b32 v76, v1, v17 offset0:128 offset1:160
	v_add_u32_e32 v0, 0x400, v76
	v_add_u32_e32 v1, 0x1000, v76
	v_add_u32_e32 v16, 0x1400, v76
	v_add_u32_e32 v17, 0x2000, v76
	v_add_u32_e32 v77, 0x2400, v76
	v_add_u32_e32 v78, 0x3000, v76
	v_add_u32_e32 v76, 0x3400, v76
	ds_write2_b32 v0, v2, v18 offset1:32
	ds_write2_b32 v0, v3, v19 offset0:128 offset1:160
	ds_write2_b32 v1, v4, v20 offset1:32
	ds_write2_b32 v1, v5, v21 offset0:128 offset1:160
	ds_write2_b32 v16, v6, v22 offset1:32
	ds_write2_b32 v16, v7, v23 offset0:128 offset1:160
	ds_write2_b32 v17, v8, v24 offset1:32
	ds_write2_b32 v17, v9, v25 offset0:128 offset1:160
	ds_write2_b32 v77, v10, v26 offset1:32
	ds_write2_b32 v77, v11, v27 offset0:128 offset1:160
	ds_write2_b32 v78, v12, v28 offset1:32
	ds_write2_b32 v78, v13, v29 offset0:128 offset1:160
	ds_write2_b32 v76, v14, v30 offset1:32
	ds_write2_b32 v76, v15, v31 offset0:128 offset1:160
	s_waitcnt vmcnt(0)
	ds_write_b32 v63, v212
	s_waitcnt vmcnt(5)
	ds_write_b32 v64, v213
	s_waitcnt vmcnt(4)
	ds_write_b32 v63, v214 offset:4128
	s_waitcnt vmcnt(3)
	ds_write_b32 v65, v215
	s_waitcnt vmcnt(2)
	ds_write_b32 v63, v216 offset:8256
	s_waitcnt vmcnt(1)
	ds_write_b32 v66, v217
	s_waitcnt vmcnt(0)
	ds_write_b32 v67, v218
	s_and_saveexec_b64 s[16:17], s[4:5]
	s_cbranch_execz .LBB0_42
	ds_write_b32 v68, v219

; #define LAS __attribute__((address_space(3)))
; __device__ __forceinline__ void p0_prologue(const Params& p, LAS unsigned char* lds) {
;     ...
;     LAS float* scr = (LAS float*)(lds + wave * 16384);
;     const int gw = blockIdx.x * NWAVES + wave, NGW = G * NWAVES;
;     constexpr int I_QK = 16 * 32, I_V = 16 * 16;
;     for (int it = gw; it < I_QK + I_V; it += NGW) {
;         int r = it;
;         if (r < I_QK) { const int kb = r >> 5, nb = r & 31; p0_transpose_item(p.w_in, 2048, 512 + nb * 32, DM, (bf16_t*)(p.ws + WS_WQK), nb * 32, nullptr, scr, kb, lane); continue; } r -= I_QK;
;         { const int kb = r >> 4, nb = r & 15; p0_transpose_item(p.w_in, 2048, 1536 + nb * 32, DM, (bf16_t*)(p.ws + WS_WA), 1024 + nb * 32, nullptr, scr, kb, lane); }
;     }
.LBB0_76:
	s_add_i32 s98, s2, 0xffffff20
	s_cmpk_lt_u32 s2, 0xe0
	s_cselect_b32 s98, 0x1000, s98
	s_mov_b32 s99, 32
	s_cmpk_eq_i32 s3, 0x100
	s_cselect_b32 s98, s98, s2
	s_cselect_b32 s99, s99, s3
	v_lshl_add_u32 v14, s98, 3, v171
	s_movk_i32 s4, 0x300
	v_cmp_gt_i32_e32 vcc, s4, v14
	s_and_saveexec_b64 s[4:5], vcc
	s_cbranch_execz .LBB0_83
	v_lshlrev_b32_e32 v1, 3, v170
	v_lshrrev_b32_e32 v15, 3, v37
	v_and_b32_e32 v1, 56, v1
	v_lshl_add_u32 v0, v171, 14, 0
	v_mul_u32_u24_e32 v2, 0x84, v1
	v_lshlrev_b32_e32 v3, 2, v15
	v_lshl_add_u32 v8, v107, 2, v0
	v_add3_u32 v16, v0, v2, v3
	v_lshlrev_b32_e32 v0, 1, v1
	v_mov_b32_e32 v1, 0
	v_lshl_add_u64 v[2:3], s[8:9], 0, v[0:1]
	v_lshl_add_u64 v[4:5], s[34:35], 0, v[0:1]
	v_lshlrev_b32_e32 v0, 2, v171
	v_mul_u32_u24_e32 v9, 0x84, v106
	v_lshl_add_u32 v20, s98, 5, v0
	v_lshlrev_b32_e32 v0, 1, v171
	s_mov_b64 s[8:9], 0x300000
	v_mov_b32_e32 v37, v1
	v_lshl_add_u32 v21, s98, 4, v0
	v_lshlrev_b32_e32 v0, 5, v171
	v_add_u32_e32 v23, v8, v9
	s_lshl_b32 s10, s99, 3
	v_or_b32_e32 v17, 8, v15
	v_or_b32_e32 v18, 16, v15
	v_or_b32_e32 v19, 24, v15
	v_lshl_add_u64 v[4:5], v[4:5], 0, s[8:9]
	s_waitcnt lgkmcnt(0)
	v_lshl_add_u64 v[6:7], s[46:47], 0, v[36:37]
	s_lshl_b32 s11, s99, 5
	s_lshl_b32 s16, s99, 4
	v_lshl_add_u32 v22, s98, 8, v0
	s_lshl_b32 s17, s99, 8
	s_mov_b64 s[8:9], 0
	s_movk_i32 s18, 0x1ff
	s_mov_b64 s[12:13], 0x1800
	s_movk_i32 s19, 0x2ff
	v_add_u32_e32 v24, 0x400, v23
	v_add_u32_e32 v25, 0x800, v23
	v_add_u32_e32 v26, 0xc00, v23
	v_add_u32_e32 v27, 0x1000, v23
	v_add_u32_e32 v28, 0x1400, v23
	v_add_u32_e32 v29, 0x1800, v23
	v_add_u32_e32 v30, 0x1c00, v23
	s_branch .LBB0_79
